# NA unit remap: workgroups 8-15 (which also run a ctx kv GEMM unit in P4) take the short top/bottom NA units
# speedup vs baseline: 1.0045x; 1.0045x over previous
.LBB0_1698:
	s_cmpk_lt_i32 s2, 0x200
	v_writelane_b32 v250, s86, 1
	s_cselect_b64 s[0:1], -1, 0
	v_writelane_b32 v250, s0, 2
	s_cmpk_gt_i32 s2, 0x1ff
	v_and_b32_e32 v160, 31, v0
	v_lshrrev_b32_e32 v1, 5, v198
	v_lshlrev_b32_e32 v178, 4, v0
	v_lshrrev_b32_e32 v147, 3, v0
	v_writelane_b32 v250, s1, 3
	v_writelane_b32 v251, s2, 61
	s_cbranch_scc1 .LBB0_1875
	v_readlane_b32 s4, v251, 48
	v_readlane_b32 s5, v251, 49
	v_readlane_b32 s6, v251, 15
	v_readlane_b32 s7, v251, 16
	v_readlane_b32 s8, v251, 52
	v_readlane_b32 s9, v251, 23
	v_readlane_b32 s10, v251, 61
	s_nop 3
	s_cmpk_lg_u32 s9, 0x100
	s_cbranch_scc1 .Lna_noremap
	s_and_b32 s36, s10, 31
	s_cmp_eq_u32 s36, 1
	s_cselect_b32 s37, 14, 0
	s_cmp_eq_u32 s36, 15
	s_cselect_b32 s37, -14, s37
	s_add_i32 s10, s10, s37
.Lna_noremap:
	s_and_b32 s11, s8, 1
	v_and_b32_e32 v216, 31, v0
	v_bfe_u32 v217, v0, 5, 1
	v_mov_b32_e32 v228, 0
	v_mov_b32_e32 v229, 0xf149f2ca
	s_lshl_b32 s36, s11, 5
	v_add_u32_e32 v222, s36, v216
	v_mul_u32_u24_e32 v199, 0x90, v222
	v_lshl_add_u32 v199, v217, 4, v199
	s_cmp_eq_u32 s11, 0
	s_cselect_b32 s37, 0, 24
	s_cselect_b32 s38, 32, 0
	v_add_u32_e32 v222, s37, v216
	v_and_b32_e32 v222, 31, v222
	v_add_u32_e32 v222, s38, v222
	v_mul_u32_u24_e32 v200, 0x90, v222
	v_lshl_add_u32 v200, v217, 4, v200
	v_mul_u32_u24_e32 v222, 0x88, v216
	v_lshl_add_u32 v222, v217, 3, v222
	v_add_u32_e32 v222, 0x4800, v222
	s_lshl_b32 s36, s11, 6
	v_add_u32_e32 v201, s36, v222
	s_cmp_eq_u32 s11, 0
	s_cselect_b32 s37, 64, 48
	s_cselect_b32 s38, 0x50, 0
	v_add_u32_e32 v202, s37, v222
	v_add_u32_e32 v203, s38, v222
	v_lshrrev_b32_e32 v222, 3, v0
	v_and_b32_e32 v223, 7, v0
	v_mul_u32_u24_e32 v204, 0x90, v222
	v_lshl_add_u32 v204, v223, 4, v204
	v_mul_u32_u24_e32 v205, 0x88, v222
	v_lshl_add_u32 v205, v223, 4, v205
	v_add_u32_e32 v205, 0x4800, v205
	v_lshlrev_b32_e32 v206, 4, v0
	v_mul_u32_u24_e32 v207, 0x2200, v222
	v_lshl_add_u32 v207, v223, 4, v207
	v_lshl_or_b32 v222, s8, 5, v216
	v_lshlrev_b32_e32 v219, 7, v222
	v_lshl_add_u32 v219, v217, 4, v219
	v_lshlrev_b32_e32 v218, 10, v222
	v_lshl_add_u32 v218, v217, 3, v218
	v_and_b32_e32 v222, 3, v216
	v_add_u32_e32 v223, 1, v222
	v_and_b32_e32 v223, 3, v223
	v_lshl_add_u32 v223, v217, 2, v223
	v_sub_u32_e32 v223, v223, v216
	v_add_u32_e32 v223, 39, v223
	v_lshlrev_b32_e32 v223, 2, v223
	v_mul_u32_u24_e32 v222, 5040, v222
	v_add_u32_e32 v208, v222, v223
	v_add_u32_e32 v208, 0x8c00, v208
	s_cmp_eq_u32 s11, 0
	s_mov_b32 s37, 0x80
	s_cselect_b32 s37, s37, 0xffffffe0
	v_add_u32_e32 v209, s37, v208
	v_mov_b32_e32 v186, 0
	v_mov_b32_e32 v187, 0
	s_lshr_b32 s36, s10, 4
	s_and_b32 s36, s36, 7
	s_mul_i32 s36, s36, 0x744
	s_add_u32 s38, s6, s36
	s_addc_u32 s39, s7, 0
	s_mov_b32 s36, 0xd00e
	v_mov_b32_e32 v222, v0
	v_mul_lo_u32 v223, v222, s36
	v_lshrrev_b32_e32 v223, 26, v223
	v_mul_u32_u24_e32 v224, 1260, v223
	v_sub_u32_e32 v224, v222, v224
	v_mul_u32_u24_e32 v225, 49933, v224
	v_lshrrev_b32_e32 v225, 22, v225
	v_mul_u32_u24_e32 v226, 84, v225
	v_sub_u32_e32 v226, v224, v226
	v_add_u32_e32 v227, 1, v223
	v_and_b32_e32 v227, 3, v227
	v_sub_u32_e32 v226, v226, v227
	v_subrev_u32_e32 v226, 24, v226
	v_cmp_gt_u32_e64 s[40:41], 31, v226
	s_nop 1
	v_cndmask_b32_e64 v227, 0, v226, s[40:41]
	v_mad_u32_u24 v227, v225, 31, v227
	v_lshlrev_b32_e32 v227, 2, v227
	global_load_dword v34, v227, s[38:39]
	v_add_u32_e32 v222, 512, v0
	v_mul_lo_u32 v223, v222, s36
	v_lshrrev_b32_e32 v223, 26, v223
	v_mul_u32_u24_e32 v224, 1260, v223
	v_sub_u32_e32 v224, v222, v224
	v_mul_u32_u24_e32 v225, 49933, v224
	v_lshrrev_b32_e32 v225, 22, v225
	v_mul_u32_u24_e32 v226, 84, v225
	v_sub_u32_e32 v226, v224, v226
	v_add_u32_e32 v227, 1, v223
	v_and_b32_e32 v227, 3, v227
	v_sub_u32_e32 v226, v226, v227
	v_subrev_u32_e32 v226, 24, v226
	v_cmp_gt_u32_e64 s[42:43], 31, v226
	s_nop 1
	v_cndmask_b32_e64 v227, 0, v226, s[42:43]
	v_mad_u32_u24 v227, v225, 31, v227
	v_lshlrev_b32_e32 v227, 2, v227
	global_load_dword v35, v227, s[38:39]
	v_add_u32_e32 v222, 1024, v0
	v_mul_lo_u32 v223, v222, s36
	v_lshrrev_b32_e32 v223, 26, v223
	v_mul_u32_u24_e32 v224, 1260, v223
	v_sub_u32_e32 v224, v222, v224
	v_mul_u32_u24_e32 v225, 49933, v224
	v_lshrrev_b32_e32 v225, 22, v225
	v_mul_u32_u24_e32 v226, 84, v225
	v_sub_u32_e32 v226, v224, v226
	v_add_u32_e32 v227, 1, v223
	v_and_b32_e32 v227, 3, v227
	v_sub_u32_e32 v226, v226, v227
	v_subrev_u32_e32 v226, 24, v226
	v_cmp_gt_u32_e64 s[44:45], 31, v226
	s_nop 1
	v_cndmask_b32_e64 v227, 0, v226, s[44:45]
	v_mad_u32_u24 v227, v225, 31, v227
	v_lshlrev_b32_e32 v227, 2, v227
	global_load_dword v36, v227, s[38:39]
	v_add_u32_e32 v222, 1536, v0
	v_mul_lo_u32 v223, v222, s36
	v_lshrrev_b32_e32 v223, 26, v223
	v_mul_u32_u24_e32 v224, 1260, v223
	v_sub_u32_e32 v224, v222, v224
	v_mul_u32_u24_e32 v225, 49933, v224
	v_lshrrev_b32_e32 v225, 22, v225
	v_mul_u32_u24_e32 v226, 84, v225
	v_sub_u32_e32 v226, v224, v226
	v_add_u32_e32 v227, 1, v223
	v_and_b32_e32 v227, 3, v227
	v_sub_u32_e32 v226, v226, v227
	v_subrev_u32_e32 v226, 24, v226
	v_cmp_gt_u32_e64 s[46:47], 31, v226
	s_nop 1
	v_cndmask_b32_e64 v227, 0, v226, s[46:47]
	v_mad_u32_u24 v227, v225, 31, v227
	v_lshlrev_b32_e32 v227, 2, v227
	global_load_dword v37, v227, s[38:39]
	v_add_u32_e32 v222, 2048, v0
	v_mul_lo_u32 v223, v222, s36
	v_lshrrev_b32_e32 v223, 26, v223
	v_mul_u32_u24_e32 v224, 1260, v223
	v_sub_u32_e32 v224, v222, v224
	v_mul_u32_u24_e32 v225, 49933, v224
	v_lshrrev_b32_e32 v225, 22, v225
	v_mul_u32_u24_e32 v226, 84, v225
	v_sub_u32_e32 v226, v224, v226
	v_add_u32_e32 v227, 1, v223
	v_and_b32_e32 v227, 3, v227
	v_sub_u32_e32 v226, v226, v227
	v_subrev_u32_e32 v226, 24, v226
	v_cmp_gt_u32_e64 s[48:49], 31, v226
	s_nop 1
	v_cndmask_b32_e64 v227, 0, v226, s[48:49]
	v_mad_u32_u24 v227, v225, 31, v227
	v_lshlrev_b32_e32 v227, 2, v227
	global_load_dword v38, v227, s[38:39]
	v_add_u32_e32 v222, 2560, v0
	v_mul_lo_u32 v223, v222, s36
	v_lshrrev_b32_e32 v223, 26, v223
	v_mul_u32_u24_e32 v224, 1260, v223
	v_sub_u32_e32 v224, v222, v224
	v_mul_u32_u24_e32 v225, 49933, v224
	v_lshrrev_b32_e32 v225, 22, v225
	v_mul_u32_u24_e32 v226, 84, v225
	v_sub_u32_e32 v226, v224, v226
	v_add_u32_e32 v227, 1, v223
	v_and_b32_e32 v227, 3, v227
	v_sub_u32_e32 v226, v226, v227
	v_subrev_u32_e32 v226, 24, v226
	v_cmp_gt_u32_e64 s[50:51], 31, v226
	s_nop 1
	v_cndmask_b32_e64 v227, 0, v226, s[50:51]
	v_mad_u32_u24 v227, v225, 31, v227
	v_lshlrev_b32_e32 v227, 2, v227
	global_load_dword v39, v227, s[38:39]
	v_add_u32_e32 v222, 3072, v0
	v_mul_lo_u32 v223, v222, s36
	v_lshrrev_b32_e32 v223, 26, v223
	v_mul_u32_u24_e32 v224, 1260, v223
	v_sub_u32_e32 v224, v222, v224
	v_mul_u32_u24_e32 v225, 49933, v224
	v_lshrrev_b32_e32 v225, 22, v225
	v_mul_u32_u24_e32 v226, 84, v225
	v_sub_u32_e32 v226, v224, v226
	v_add_u32_e32 v227, 1, v223
	v_and_b32_e32 v227, 3, v227
	v_sub_u32_e32 v226, v226, v227
	v_subrev_u32_e32 v226, 24, v226
	v_cmp_gt_u32_e64 s[52:53], 31, v226
	s_nop 1
	v_cndmask_b32_e64 v227, 0, v226, s[52:53]
	v_mad_u32_u24 v227, v225, 31, v227
	v_lshlrev_b32_e32 v227, 2, v227
	global_load_dword v40, v227, s[38:39]
	v_add_u32_e32 v222, 3584, v0
	v_mul_lo_u32 v223, v222, s36
	v_lshrrev_b32_e32 v223, 26, v223
	v_mul_u32_u24_e32 v224, 1260, v223
	v_sub_u32_e32 v224, v222, v224
	v_mul_u32_u24_e32 v225, 49933, v224
	v_lshrrev_b32_e32 v225, 22, v225
	v_mul_u32_u24_e32 v226, 84, v225
	v_sub_u32_e32 v226, v224, v226
	v_add_u32_e32 v227, 1, v223
	v_and_b32_e32 v227, 3, v227
	v_sub_u32_e32 v226, v226, v227
	v_subrev_u32_e32 v226, 24, v226
	v_cmp_gt_u32_e64 s[54:55], 31, v226
	s_nop 1
	v_cndmask_b32_e64 v227, 0, v226, s[54:55]
	v_mad_u32_u24 v227, v225, 31, v227
	v_lshlrev_b32_e32 v227, 2, v227
	global_load_dword v41, v227, s[38:39]
	v_add_u32_e32 v222, 4096, v0
	v_mul_lo_u32 v223, v222, s36
	v_lshrrev_b32_e32 v223, 26, v223
	v_mul_u32_u24_e32 v224, 1260, v223
	v_sub_u32_e32 v224, v222, v224
	v_mul_u32_u24_e32 v225, 49933, v224
	v_lshrrev_b32_e32 v225, 22, v225
	v_mul_u32_u24_e32 v226, 84, v225
	v_sub_u32_e32 v226, v224, v226
	v_add_u32_e32 v227, 1, v223
	v_and_b32_e32 v227, 3, v227
	v_sub_u32_e32 v226, v226, v227
	v_subrev_u32_e32 v226, 24, v226
	v_cmp_gt_u32_e64 s[56:57], 31, v226
	s_nop 1
	v_cndmask_b32_e64 v227, 0, v226, s[56:57]
	v_mad_u32_u24 v227, v225, 31, v227
	v_lshlrev_b32_e32 v227, 2, v227
	global_load_dword v42, v227, s[38:39]
	v_add_u32_e32 v222, 4608, v0
	v_mul_lo_u32 v223, v222, s36
	v_lshrrev_b32_e32 v223, 26, v223
	v_mul_u32_u24_e32 v224, 1260, v223
	v_sub_u32_e32 v224, v222, v224
	v_mul_u32_u24_e32 v225, 49933, v224
	v_lshrrev_b32_e32 v225, 22, v225
	v_mul_u32_u24_e32 v226, 84, v225
	v_sub_u32_e32 v226, v224, v226
	v_add_u32_e32 v227, 1, v223
	v_and_b32_e32 v227, 3, v227
	v_sub_u32_e32 v226, v226, v227
	v_subrev_u32_e32 v226, 24, v226
	v_cmp_gt_u32_e64 s[58:59], 31, v226
	s_nop 1
	v_cndmask_b32_e64 v227, 0, v226, s[58:59]
	v_mad_u32_u24 v227, v225, 31, v227
	v_lshlrev_b32_e32 v227, 2, v227
	global_load_dword v43, v227, s[38:39]
	v_lshlrev_b32_e32 v222, 2, v0
	s_waitcnt vmcnt(0)
	v_mul_f32_e32 v34, 0x3fb8aa3b, v34
	v_cndmask_b32_e64 v34, 0, v34, s[40:41]
	v_mul_f32_e32 v35, 0x3fb8aa3b, v35
	v_cndmask_b32_e64 v35, 0, v35, s[42:43]
	v_mul_f32_e32 v36, 0x3fb8aa3b, v36
	v_cndmask_b32_e64 v36, 0, v36, s[44:45]
	v_mul_f32_e32 v37, 0x3fb8aa3b, v37
	v_cndmask_b32_e64 v37, 0, v37, s[46:47]
	v_mul_f32_e32 v38, 0x3fb8aa3b, v38
	v_cndmask_b32_e64 v38, 0, v38, s[48:49]
	v_mul_f32_e32 v39, 0x3fb8aa3b, v39
	v_cndmask_b32_e64 v39, 0, v39, s[50:51]
	v_mul_f32_e32 v40, 0x3fb8aa3b, v40
	v_cndmask_b32_e64 v40, 0, v40, s[52:53]
	v_mul_f32_e32 v41, 0x3fb8aa3b, v41
	v_cndmask_b32_e64 v41, 0, v41, s[54:55]
	v_mul_f32_e32 v42, 0x3fb8aa3b, v42
	v_cndmask_b32_e64 v42, 0, v42, s[56:57]
	v_mul_f32_e32 v43, 0x3fb8aa3b, v43
	v_cndmask_b32_e64 v43, 0, v43, s[58:59]
	v_cmp_gt_u32_e32 vcc, 432, v0
	ds_write_b32 v222, v34 offset:35840
	ds_write_b32 v222, v35 offset:37888
	ds_write_b32 v222, v36 offset:39936
	ds_write_b32 v222, v37 offset:41984
	ds_write_b32 v222, v38 offset:44032
	ds_write_b32 v222, v39 offset:46080
	ds_write_b32 v222, v40 offset:48128
	ds_write_b32 v222, v41 offset:50176
	ds_write_b32 v222, v42 offset:52224
	s_and_saveexec_b64 s[60:61], vcc
	ds_write_b32 v222, v43 offset:54272
	s_mov_b64 exec, s[60:61]
